# v12 + out-projection epilogue: residual loads triple-buffered three row steps ahead with counted vmcnt waits
# speedup vs baseline: 1.0162x; 1.0041x over previous
.LBB0_1681:
	v_lshl_or_b32 v146, s8, 8, v154
	v_ashrrev_i32_e32 v147, 31, v146
	v_lshlrev_b64 v[146:147], 2, v[146:147]
	v_lshl_add_u64 v[166:167], v[150:151], 0, v[146:147]
	v_mov_b64_e32 v[220:221], v[166:167]
	global_load_dwordx4 v[170:173], v[220:221], off
	global_load_dwordx4 v[174:177], v[220:221], off offset:16
	global_load_dwordx4 v[178:181], v[220:221], off offset:512
	global_load_dwordx4 v[182:185], v[220:221], off offset:528
	s_mov_b64 s[100:101], 0x10000
	v_lshl_add_u64 v[218:219], v[220:221], 0, s[100:101]
	global_load_dwordx4 v[186:189], v[218:219], off
	global_load_dwordx4 v[190:193], v[218:219], off offset:16
	global_load_dwordx4 v[194:197], v[218:219], off offset:512
	global_load_dwordx4 v[198:201], v[218:219], off offset:528
	s_mov_b64 s[100:101], 0x20000
	v_lshl_add_u64 v[218:219], v[220:221], 0, s[100:101]
	global_load_dwordx4 v[202:205], v[218:219], off
	global_load_dwordx4 v[206:209], v[218:219], off offset:16
	global_load_dwordx4 v[210:213], v[218:219], off offset:512
	global_load_dwordx4 v[214:217], v[218:219], off offset:528
	v_lshl_add_u64 v[148:149], s[0:1], 0, v[148:149]
	v_lshl_add_u64 v[168:169], v[148:149], 0, v[146:147]
	s_lshl_b32 s8, s8, 2
	s_ashr_i32 s9, s8, 31
	s_or_b64 s[52:53], s[8:9], s[16:17]
	s_waitcnt vmcnt(11)
	v_pk_fma_f32 v[126:127], v[172:173], s[26:27], v[126:127] op_sel_hi:[1,0,1]
	v_pk_fma_f32 v[124:125], v[170:171], s[26:27], v[124:125] op_sel_hi:[1,0,1]
	s_waitcnt vmcnt(10)
	v_pk_fma_f32 v[122:123], v[176:177], s[26:27], v[122:123] op_sel_hi:[1,0,1]
	v_pk_fma_f32 v[120:121], v[174:175], s[26:27], v[120:121] op_sel_hi:[1,0,1]
	global_store_dwordx4 v[168:169], v[124:127], off
	global_store_dwordx4 v[168:169], v[120:123], off offset:16
	v_add_f32_e32 v162, v124, v125
	v_add_f32_e32 v163, v126, v127
	v_mul_f32_e32 v125, v125, v125
	v_mul_f32_e32 v127, v127, v127
	v_add_f32_e32 v164, v120, v121
	v_add_f32_e32 v165, v122, v123
	v_mul_f32_e32 v121, v121, v121
	v_mul_f32_e32 v123, v123, v123
	v_fmac_f32_e32 v125, v124, v124
	v_fmac_f32_e32 v127, v126, v126
	v_fmac_f32_e32 v121, v120, v120
	v_fmac_f32_e32 v123, v122, v122
	v_add_f32_e32 v122, v125, v127
	v_add_f32_e32 v121, v122, v121
	v_add_f32_e32 v121, v123, v121
	v_add_f32_e32 v162, v162, v163
	v_add_f32_e32 v120, v162, v164
	v_add_f32_e32 v120, v165, v120
	v_add_f32_e32 v120, 0, v120
	s_waitcnt vmcnt(11)
	v_pk_fma_f32 v[118:119], v[180:181], s[26:27], v[118:119] op_sel_hi:[1,0,1]
	v_pk_fma_f32 v[116:117], v[178:179], s[26:27], v[116:117] op_sel_hi:[1,0,1]
	s_waitcnt vmcnt(10)
	v_pk_fma_f32 v[114:115], v[184:185], s[26:27], v[114:115] op_sel_hi:[1,0,1]
	v_pk_fma_f32 v[112:113], v[182:183], s[26:27], v[112:113] op_sel_hi:[1,0,1]
	global_store_dwordx4 v[168:169], v[116:119], off offset:512
	global_store_dwordx4 v[168:169], v[112:115], off offset:528
	v_add_f32_e32 v122, v116, v117
	v_add_f32_e32 v123, v118, v119
	v_mul_f32_e32 v117, v117, v117
	v_mul_f32_e32 v119, v119, v119
	v_add_f32_e32 v124, v112, v113
	v_add_f32_e32 v125, v114, v115
	v_mul_f32_e32 v113, v113, v113
	v_mul_f32_e32 v115, v115, v115
	v_fmac_f32_e32 v117, v116, v116
	v_fmac_f32_e32 v119, v118, v118
	v_add_f32_e32 v122, v122, v123
	v_fmac_f32_e32 v113, v112, v112
	v_fmac_f32_e32 v115, v114, v114
	v_add_f32_e32 v114, v117, v119
	v_add_f32_e32 v112, v122, v124
	v_add_f32_e32 v113, v114, v113
	v_add_f32_e32 v112, v125, v112
	v_add_f32_e32 v113, v115, v113
	v_add_f32_e32 v112, v120, v112
	v_add_f32_e32 v113, v121, v113
	v_mov_b32_e32 v114, v112
	v_mov_b32_e32 v115, v113
	s_nop 0
	v_permlane16_swap_b32_e32 v112, v114
	v_permlane16_swap_b32_e32 v113, v115
	v_add_f32_e32 v112, v112, v114
	v_add_f32_e32 v113, v113, v115
	v_mov_b32_e32 v114, v112
	v_mov_b32_e32 v115, v113
	s_nop 0
	v_permlane32_swap_b32_e32 v112, v114
	v_permlane32_swap_b32_e32 v113, v115
	s_and_saveexec_b64 s[8:9], s[4:5]
	s_cbranch_execz .LBB0_1683
	v_lshlrev_b64 v[116:117], 7, v[144:145]
	v_lshl_add_u64 v[116:117], s[14:15], 0, v[116:117]
	v_lshl_add_u64 v[116:117], s[52:53], 3, v[116:117]
	v_pk_add_f32 v[112:113], v[112:113], v[114:115]
	global_store_dwordx2 v[116:117], v[112:113], off
.LBB0_1683:
	s_or_b64 exec, exec, s[8:9]
	s_mov_b64 s[100:101], 0x30000
	v_lshl_add_u64 v[218:219], v[220:221], 0, s[100:101]
	global_load_dwordx4 v[170:173], v[218:219], off
	global_load_dwordx4 v[174:177], v[218:219], off offset:16
	global_load_dwordx4 v[178:181], v[218:219], off offset:512
	global_load_dwordx4 v[182:185], v[218:219], off offset:528
	v_or_b32_e32 v112, 16, v144
	v_cndmask_b32_e64 v113, 0, 1, s[54:55]
	s_mov_b64 s[56:57], -1
	v_cmp_ne_u32_e64 s[8:9], 1, v113
	s_andn2_b64 vcc, exec, s[54:55]
	v_ashrrev_i32_e32 v113, 31, v112
	s_cbranch_vccnz .LBB0_1685
	v_readlane_b32 s36, v251, 3
	v_lshlrev_b64 v[114:115], 12, v[112:113]
	v_readlane_b32 s37, v251, 4
	s_mov_b64 s[56:57], 0
	v_readlane_b32 s38, v251, 5
	v_lshl_add_u64 v[116:117], s[36:37], 0, v[114:115]
	v_readlane_b32 s39, v251, 6
	v_readlane_b32 s40, v251, 7
	v_readlane_b32 s41, v251, 8
	v_readlane_b32 s42, v251, 9
	v_readlane_b32 s43, v251, 10
	v_readlane_b32 s44, v251, 11
	v_readlane_b32 s45, v251, 12
	v_readlane_b32 s46, v251, 13
	v_readlane_b32 s47, v251, 14
	v_readlane_b32 s48, v251, 15
	v_readlane_b32 s49, v251, 16
	v_readlane_b32 s50, v251, 17
	v_readlane_b32 s51, v251, 18

.LBB0_1687:
	v_lshl_add_u64 v[124:125], v[116:117], 0, v[146:147]
	v_lshl_add_u64 v[114:115], s[0:1], 0, v[114:115]
	v_lshl_add_u64 v[126:127], v[114:115], 0, v[146:147]
	s_waitcnt vmcnt(16)
	v_pk_fma_f32 v[110:111], v[188:189], s[26:27], v[110:111] op_sel_hi:[1,0,1]
	v_pk_fma_f32 v[108:109], v[186:187], s[26:27], v[108:109] op_sel_hi:[1,0,1]
	s_waitcnt vmcnt(15)
	v_pk_fma_f32 v[106:107], v[192:193], s[26:27], v[106:107] op_sel_hi:[1,0,1]
	v_pk_fma_f32 v[104:105], v[190:191], s[26:27], v[104:105] op_sel_hi:[1,0,1]
	global_store_dwordx4 v[126:127], v[108:111], off
	global_store_dwordx4 v[126:127], v[104:107], off offset:16
	v_add_f32_e32 v122, v108, v109
	v_add_f32_e32 v123, v110, v111
	v_mul_f32_e32 v109, v109, v109
	v_mul_f32_e32 v111, v111, v111
	v_add_f32_e32 v124, v104, v105
	v_add_f32_e32 v125, v106, v107
	v_mul_f32_e32 v105, v105, v105
	v_mul_f32_e32 v107, v107, v107
	v_fmac_f32_e32 v109, v108, v108
	v_fmac_f32_e32 v111, v110, v110
	v_fmac_f32_e32 v105, v104, v104
	v_fmac_f32_e32 v107, v106, v106
	v_add_f32_e32 v106, v109, v111
	v_add_f32_e32 v105, v106, v105
	v_add_f32_e32 v105, v107, v105
	v_add_f32_e32 v122, v122, v123
	v_add_f32_e32 v104, v122, v124
	v_add_f32_e32 v104, v125, v104
	v_add_f32_e32 v104, 0, v104
	s_waitcnt vmcnt(16)
	v_pk_fma_f32 v[102:103], v[196:197], s[26:27], v[102:103] op_sel_hi:[1,0,1]
	v_pk_fma_f32 v[100:101], v[194:195], s[26:27], v[100:101] op_sel_hi:[1,0,1]
	s_waitcnt vmcnt(15)
	v_pk_fma_f32 v[98:99], v[200:201], s[26:27], v[98:99] op_sel_hi:[1,0,1]
	v_pk_fma_f32 v[96:97], v[198:199], s[26:27], v[96:97] op_sel_hi:[1,0,1]
	global_store_dwordx4 v[126:127], v[100:103], off offset:512
	global_store_dwordx4 v[126:127], v[96:99], off offset:528
	v_add_f32_e32 v106, v100, v101
	v_add_f32_e32 v107, v102, v103
	v_mul_f32_e32 v101, v101, v101
	v_mul_f32_e32 v103, v103, v103
	v_add_f32_e32 v108, v96, v97
	v_add_f32_e32 v109, v98, v99
	v_mul_f32_e32 v97, v97, v97
	v_mul_f32_e32 v99, v99, v99
	v_fmac_f32_e32 v101, v100, v100
	v_fmac_f32_e32 v103, v102, v102
	v_add_f32_e32 v106, v106, v107
	v_fmac_f32_e32 v97, v96, v96
	v_fmac_f32_e32 v99, v98, v98
	v_add_f32_e32 v98, v101, v103
	v_add_f32_e32 v96, v106, v108
	v_add_f32_e32 v97, v98, v97
	v_add_f32_e32 v96, v109, v96
	v_add_f32_e32 v97, v99, v97
	v_add_f32_e32 v96, v104, v96
	v_add_f32_e32 v97, v105, v97
	v_mov_b32_e32 v98, v96
	v_mov_b32_e32 v99, v97
	s_nop 0
	v_permlane16_swap_b32_e32 v96, v98
	v_permlane16_swap_b32_e32 v97, v99
	v_add_f32_e32 v96, v96, v98
	v_add_f32_e32 v97, v97, v99
	v_mov_b32_e32 v98, v96
	v_mov_b32_e32 v99, v97
	s_nop 0
	v_permlane32_swap_b32_e32 v96, v98
	v_permlane32_swap_b32_e32 v97, v99
	s_and_saveexec_b64 s[54:55], s[4:5]
	s_cbranch_execz .LBB0_1689
	v_lshlrev_b64 v[100:101], 7, v[112:113]
	v_lshl_add_u64 v[100:101], s[14:15], 0, v[100:101]
	v_lshl_add_u64 v[100:101], s[52:53], 3, v[100:101]
	v_pk_add_f32 v[96:97], v[96:97], v[98:99]
	global_store_dwordx2 v[100:101], v[96:97], off
.LBB0_1689:
	s_or_b64 exec, exec, s[54:55]
	s_mov_b64 s[100:101], 0x80000
	v_lshl_add_u64 v[218:219], v[220:221], 0, s[100:101]
	global_load_dwordx4 v[186:189], v[218:219], off
	global_load_dwordx4 v[190:193], v[218:219], off offset:16
	global_load_dwordx4 v[194:197], v[218:219], off offset:512
	global_load_dwordx4 v[198:201], v[218:219], off offset:528
	v_or_b32_e32 v96, 32, v144
	s_mov_b64 s[54:55], -1
	s_and_b64 vcc, exec, s[8:9]
	v_ashrrev_i32_e32 v97, 31, v96
	s_cbranch_vccnz .LBB0_1691
	v_readlane_b32 s36, v251, 3
	v_lshlrev_b64 v[98:99], 12, v[96:97]
	v_readlane_b32 s37, v251, 4
	s_mov_b64 s[54:55], 0
	v_readlane_b32 s38, v251, 5
	v_lshl_add_u64 v[100:101], s[36:37], 0, v[98:99]
	v_readlane_b32 s39, v251, 6
	v_readlane_b32 s40, v251, 7
	v_readlane_b32 s41, v251, 8
	v_readlane_b32 s42, v251, 9
	v_readlane_b32 s43, v251, 10
	v_readlane_b32 s44, v251, 11
	v_readlane_b32 s45, v251, 12
	v_readlane_b32 s46, v251, 13
	v_readlane_b32 s47, v251, 14
	v_readlane_b32 s48, v251, 15
	v_readlane_b32 s49, v251, 16
	v_readlane_b32 s50, v251, 17
	v_readlane_b32 s51, v251, 18

.LBB0_1693:
	v_lshl_add_u64 v[108:109], v[100:101], 0, v[146:147]
	v_lshl_add_u64 v[98:99], s[0:1], 0, v[98:99]
	v_lshl_add_u64 v[110:111], v[98:99], 0, v[146:147]
	s_waitcnt vmcnt(21)
	v_pk_fma_f32 v[94:95], v[204:205], s[26:27], v[94:95] op_sel_hi:[1,0,1]
	v_pk_fma_f32 v[92:93], v[202:203], s[26:27], v[92:93] op_sel_hi:[1,0,1]
	s_waitcnt vmcnt(20)
	v_pk_fma_f32 v[90:91], v[208:209], s[26:27], v[90:91] op_sel_hi:[1,0,1]
	v_pk_fma_f32 v[88:89], v[206:207], s[26:27], v[88:89] op_sel_hi:[1,0,1]
	global_store_dwordx4 v[110:111], v[92:95], off
	global_store_dwordx4 v[110:111], v[88:91], off offset:16
	v_add_f32_e32 v106, v92, v93
	v_add_f32_e32 v107, v94, v95
	v_mul_f32_e32 v93, v93, v93
	v_mul_f32_e32 v95, v95, v95
	v_add_f32_e32 v108, v88, v89
	v_add_f32_e32 v109, v90, v91
	v_mul_f32_e32 v89, v89, v89
	v_mul_f32_e32 v91, v91, v91
	v_fmac_f32_e32 v93, v92, v92
	v_fmac_f32_e32 v95, v94, v94
	v_fmac_f32_e32 v89, v88, v88
	v_fmac_f32_e32 v91, v90, v90
	v_add_f32_e32 v90, v93, v95
	v_add_f32_e32 v89, v90, v89
	v_add_f32_e32 v89, v91, v89
	v_add_f32_e32 v106, v106, v107
	v_add_f32_e32 v88, v106, v108
	v_add_f32_e32 v88, v109, v88
	v_add_f32_e32 v88, 0, v88
	s_waitcnt vmcnt(21)
	v_pk_fma_f32 v[86:87], v[212:213], s[26:27], v[86:87] op_sel_hi:[1,0,1]
	v_pk_fma_f32 v[84:85], v[210:211], s[26:27], v[84:85] op_sel_hi:[1,0,1]
	s_waitcnt vmcnt(20)
	v_pk_fma_f32 v[82:83], v[216:217], s[26:27], v[82:83] op_sel_hi:[1,0,1]
	v_pk_fma_f32 v[80:81], v[214:215], s[26:27], v[80:81] op_sel_hi:[1,0,1]
	global_store_dwordx4 v[110:111], v[84:87], off offset:512
	global_store_dwordx4 v[110:111], v[80:83], off offset:528
	v_add_f32_e32 v90, v84, v85
	v_add_f32_e32 v91, v86, v87
	v_mul_f32_e32 v85, v85, v85
	v_mul_f32_e32 v87, v87, v87
	v_add_f32_e32 v92, v80, v81
	v_add_f32_e32 v93, v82, v83
	v_mul_f32_e32 v81, v81, v81
	v_mul_f32_e32 v83, v83, v83
	v_fmac_f32_e32 v85, v84, v84
	v_fmac_f32_e32 v87, v86, v86
	v_add_f32_e32 v90, v90, v91
	v_fmac_f32_e32 v81, v80, v80
	v_fmac_f32_e32 v83, v82, v82
	v_add_f32_e32 v82, v85, v87
	v_add_f32_e32 v80, v90, v92
	v_add_f32_e32 v81, v82, v81
	v_add_f32_e32 v80, v93, v80
	v_add_f32_e32 v81, v83, v81
	v_add_f32_e32 v80, v88, v80
	v_add_f32_e32 v81, v89, v81
	v_mov_b32_e32 v82, v80
	v_mov_b32_e32 v83, v81
	s_nop 0
	v_permlane16_swap_b32_e32 v80, v82
	v_permlane16_swap_b32_e32 v81, v83
	v_add_f32_e32 v80, v80, v82
	v_add_f32_e32 v81, v81, v83
	v_mov_b32_e32 v82, v80
	v_mov_b32_e32 v83, v81
	s_nop 0
	v_permlane32_swap_b32_e32 v80, v82
	v_permlane32_swap_b32_e32 v81, v83
	s_and_saveexec_b64 s[54:55], s[4:5]
	s_cbranch_execz .LBB0_1695
	v_lshlrev_b64 v[84:85], 7, v[96:97]
	v_lshl_add_u64 v[84:85], s[14:15], 0, v[84:85]
	v_lshl_add_u64 v[84:85], s[52:53], 3, v[84:85]
	v_pk_add_f32 v[80:81], v[80:81], v[82:83]
	global_store_dwordx2 v[84:85], v[80:81], off
.LBB0_1695:
	s_or_b64 exec, exec, s[54:55]
	s_mov_b64 s[100:101], 0x90000
	v_lshl_add_u64 v[218:219], v[220:221], 0, s[100:101]
	global_load_dwordx4 v[202:205], v[218:219], off
	global_load_dwordx4 v[206:209], v[218:219], off offset:16
	global_load_dwordx4 v[210:213], v[218:219], off offset:512
	global_load_dwordx4 v[214:217], v[218:219], off offset:528
	v_or_b32_e32 v80, 48, v144
	s_mov_b64 s[54:55], -1
	s_and_b64 vcc, exec, s[8:9]
	v_ashrrev_i32_e32 v81, 31, v80
	s_cbranch_vccnz .LBB0_1697
	v_readlane_b32 s36, v251, 3
	v_lshlrev_b64 v[82:83], 12, v[80:81]
	v_readlane_b32 s37, v251, 4
	s_mov_b64 s[54:55], 0
	v_readlane_b32 s38, v251, 5
	v_lshl_add_u64 v[84:85], s[36:37], 0, v[82:83]
	v_readlane_b32 s39, v251, 6
	v_readlane_b32 s40, v251, 7
	v_readlane_b32 s41, v251, 8
	v_readlane_b32 s42, v251, 9
	v_readlane_b32 s43, v251, 10
	v_readlane_b32 s44, v251, 11
	v_readlane_b32 s45, v251, 12
	v_readlane_b32 s46, v251, 13
	v_readlane_b32 s47, v251, 14
	v_readlane_b32 s48, v251, 15
	v_readlane_b32 s49, v251, 16
	v_readlane_b32 s50, v251, 17
	v_readlane_b32 s51, v251, 18

.LBB0_1699:
	v_lshl_add_u64 v[92:93], v[84:85], 0, v[146:147]
	v_lshl_add_u64 v[82:83], s[0:1], 0, v[82:83]
	v_lshl_add_u64 v[94:95], v[82:83], 0, v[146:147]
	s_waitcnt vmcnt(21)
	v_pk_fma_f32 v[78:79], v[172:173], s[26:27], v[78:79] op_sel_hi:[1,0,1]
	v_pk_fma_f32 v[76:77], v[170:171], s[26:27], v[76:77] op_sel_hi:[1,0,1]
	s_waitcnt vmcnt(20)
	v_pk_fma_f32 v[74:75], v[176:177], s[26:27], v[74:75] op_sel_hi:[1,0,1]
	v_pk_fma_f32 v[72:73], v[174:175], s[26:27], v[72:73] op_sel_hi:[1,0,1]
	global_store_dwordx4 v[94:95], v[76:79], off
	global_store_dwordx4 v[94:95], v[72:75], off offset:16
	v_add_f32_e32 v90, v76, v77
	v_add_f32_e32 v91, v78, v79
	v_mul_f32_e32 v77, v77, v77
	v_mul_f32_e32 v79, v79, v79
	v_add_f32_e32 v92, v72, v73
	v_add_f32_e32 v93, v74, v75
	v_mul_f32_e32 v73, v73, v73
	v_mul_f32_e32 v75, v75, v75
	v_fmac_f32_e32 v77, v76, v76
	v_fmac_f32_e32 v79, v78, v78
	v_fmac_f32_e32 v73, v72, v72
	v_fmac_f32_e32 v75, v74, v74
	v_add_f32_e32 v74, v77, v79
	v_add_f32_e32 v73, v74, v73
	v_add_f32_e32 v73, v75, v73
	v_add_f32_e32 v90, v90, v91
	v_add_f32_e32 v72, v90, v92
	v_add_f32_e32 v72, v93, v72
	v_add_f32_e32 v72, 0, v72
	s_waitcnt vmcnt(21)
	v_pk_fma_f32 v[70:71], v[180:181], s[26:27], v[70:71] op_sel_hi:[1,0,1]
	v_pk_fma_f32 v[68:69], v[178:179], s[26:27], v[68:69] op_sel_hi:[1,0,1]
	s_waitcnt vmcnt(20)
	v_pk_fma_f32 v[66:67], v[184:185], s[26:27], v[66:67] op_sel_hi:[1,0,1]
	v_pk_fma_f32 v[64:65], v[182:183], s[26:27], v[64:65] op_sel_hi:[1,0,1]
	global_store_dwordx4 v[94:95], v[68:71], off offset:512
	global_store_dwordx4 v[94:95], v[64:67], off offset:528
	v_add_f32_e32 v74, v68, v69
	v_add_f32_e32 v75, v70, v71
	v_mul_f32_e32 v69, v69, v69
	v_mul_f32_e32 v71, v71, v71
	v_add_f32_e32 v76, v64, v65
	v_add_f32_e32 v77, v66, v67
	v_mul_f32_e32 v65, v65, v65
	v_mul_f32_e32 v67, v67, v67
	v_fmac_f32_e32 v69, v68, v68
	v_fmac_f32_e32 v71, v70, v70
	v_add_f32_e32 v74, v74, v75
	v_fmac_f32_e32 v65, v64, v64
	v_fmac_f32_e32 v67, v66, v66
	v_add_f32_e32 v66, v69, v71
	v_add_f32_e32 v64, v74, v76
	v_add_f32_e32 v65, v66, v65
	v_add_f32_e32 v64, v77, v64
	v_add_f32_e32 v65, v67, v65
	v_add_f32_e32 v64, v72, v64
	v_add_f32_e32 v65, v73, v65
	v_mov_b32_e32 v66, v64
	v_mov_b32_e32 v67, v65
	s_nop 0
	v_permlane16_swap_b32_e32 v64, v66
	v_permlane16_swap_b32_e32 v65, v67
	v_add_f32_e32 v64, v64, v66
	v_add_f32_e32 v65, v65, v67
	v_mov_b32_e32 v66, v64
	v_mov_b32_e32 v67, v65
	s_nop 0
	v_permlane32_swap_b32_e32 v64, v66
	v_permlane32_swap_b32_e32 v65, v67
	s_and_saveexec_b64 s[54:55], s[4:5]
	s_cbranch_execz .LBB0_1701
	v_lshlrev_b64 v[68:69], 7, v[80:81]
	v_lshl_add_u64 v[68:69], s[14:15], 0, v[68:69]
	v_lshl_add_u64 v[68:69], s[52:53], 3, v[68:69]
	v_pk_add_f32 v[64:65], v[64:65], v[66:67]
	global_store_dwordx2 v[68:69], v[64:65], off
.LBB0_1701:
	s_or_b64 exec, exec, s[54:55]
	s_mov_b64 s[100:101], 0xa0000
	v_lshl_add_u64 v[218:219], v[220:221], 0, s[100:101]
	global_load_dwordx4 v[170:173], v[218:219], off
	global_load_dwordx4 v[174:177], v[218:219], off offset:16
	global_load_dwordx4 v[178:181], v[218:219], off offset:512
	global_load_dwordx4 v[182:185], v[218:219], off offset:528
	v_add_u32_e32 v64, 0x80, v144
	s_mov_b64 s[54:55], -1
	s_and_b64 vcc, exec, s[8:9]
	v_ashrrev_i32_e32 v65, 31, v64
	s_cbranch_vccnz .LBB0_1703
	v_readlane_b32 s36, v251, 3
	v_lshlrev_b64 v[66:67], 12, v[64:65]
	v_readlane_b32 s37, v251, 4
	s_mov_b64 s[54:55], 0
	v_readlane_b32 s38, v251, 5
	v_lshl_add_u64 v[68:69], s[36:37], 0, v[66:67]
	v_readlane_b32 s39, v251, 6
	v_readlane_b32 s40, v251, 7
	v_readlane_b32 s41, v251, 8
	v_readlane_b32 s42, v251, 9
	v_readlane_b32 s43, v251, 10
	v_readlane_b32 s44, v251, 11
	v_readlane_b32 s45, v251, 12
	v_readlane_b32 s46, v251, 13
	v_readlane_b32 s47, v251, 14
	v_readlane_b32 s48, v251, 15
	v_readlane_b32 s49, v251, 16
	v_readlane_b32 s50, v251, 17
	v_readlane_b32 s51, v251, 18

.LBB0_1705:
	v_lshl_add_u64 v[76:77], v[68:69], 0, v[146:147]
	v_lshl_add_u64 v[66:67], s[0:1], 0, v[66:67]
	v_lshl_add_u64 v[78:79], v[66:67], 0, v[146:147]
	s_waitcnt vmcnt(21)
	v_pk_fma_f32 v[62:63], v[188:189], s[26:27], v[62:63] op_sel_hi:[1,0,1]
	v_pk_fma_f32 v[60:61], v[186:187], s[26:27], v[60:61] op_sel_hi:[1,0,1]
	s_waitcnt vmcnt(20)
	v_pk_fma_f32 v[58:59], v[192:193], s[26:27], v[58:59] op_sel_hi:[1,0,1]
	v_pk_fma_f32 v[56:57], v[190:191], s[26:27], v[56:57] op_sel_hi:[1,0,1]
	global_store_dwordx4 v[78:79], v[60:63], off
	global_store_dwordx4 v[78:79], v[56:59], off offset:16
	v_add_f32_e32 v74, v60, v61
	v_add_f32_e32 v75, v62, v63
	v_mul_f32_e32 v61, v61, v61
	v_mul_f32_e32 v63, v63, v63
	v_add_f32_e32 v76, v56, v57
	v_add_f32_e32 v77, v58, v59
	v_mul_f32_e32 v57, v57, v57
	v_mul_f32_e32 v59, v59, v59
	v_fmac_f32_e32 v61, v60, v60
	v_fmac_f32_e32 v63, v62, v62
	v_fmac_f32_e32 v57, v56, v56
	v_fmac_f32_e32 v59, v58, v58
	v_add_f32_e32 v58, v61, v63
	v_add_f32_e32 v57, v58, v57
	v_add_f32_e32 v57, v59, v57
	v_add_f32_e32 v74, v74, v75
	v_add_f32_e32 v56, v74, v76
	v_add_f32_e32 v56, v77, v56
	v_add_f32_e32 v56, 0, v56
	s_waitcnt vmcnt(21)
	v_pk_fma_f32 v[54:55], v[196:197], s[26:27], v[54:55] op_sel_hi:[1,0,1]
	v_pk_fma_f32 v[52:53], v[194:195], s[26:27], v[52:53] op_sel_hi:[1,0,1]
	s_waitcnt vmcnt(20)
	v_pk_fma_f32 v[50:51], v[200:201], s[26:27], v[50:51] op_sel_hi:[1,0,1]
	v_pk_fma_f32 v[48:49], v[198:199], s[26:27], v[48:49] op_sel_hi:[1,0,1]
	global_store_dwordx4 v[78:79], v[52:55], off offset:512
	global_store_dwordx4 v[78:79], v[48:51], off offset:528
	v_add_f32_e32 v58, v52, v53
	v_add_f32_e32 v59, v54, v55
	v_mul_f32_e32 v53, v53, v53
	v_mul_f32_e32 v55, v55, v55
	v_add_f32_e32 v60, v48, v49
	v_add_f32_e32 v61, v50, v51
	v_mul_f32_e32 v49, v49, v49
	v_mul_f32_e32 v51, v51, v51
	v_fmac_f32_e32 v53, v52, v52
	v_fmac_f32_e32 v55, v54, v54
	v_add_f32_e32 v58, v58, v59
	v_fmac_f32_e32 v49, v48, v48
	v_fmac_f32_e32 v51, v50, v50
	v_add_f32_e32 v50, v53, v55
	v_add_f32_e32 v48, v58, v60
	v_add_f32_e32 v49, v50, v49
	v_add_f32_e32 v48, v61, v48
	v_add_f32_e32 v49, v51, v49
	v_add_f32_e32 v48, v56, v48
	v_add_f32_e32 v49, v57, v49
	v_mov_b32_e32 v50, v48
	v_mov_b32_e32 v51, v49
	s_nop 0
	v_permlane16_swap_b32_e32 v48, v50
	v_permlane16_swap_b32_e32 v49, v51
	v_add_f32_e32 v48, v48, v50
	v_add_f32_e32 v49, v49, v51
	v_mov_b32_e32 v50, v48
	v_mov_b32_e32 v51, v49
	s_nop 0
	v_permlane32_swap_b32_e32 v48, v50
	v_permlane32_swap_b32_e32 v49, v51
	s_and_saveexec_b64 s[54:55], s[4:5]
	s_cbranch_execz .LBB0_1707
	v_lshlrev_b64 v[52:53], 7, v[64:65]
	v_lshl_add_u64 v[52:53], s[14:15], 0, v[52:53]
	v_lshl_add_u64 v[52:53], s[52:53], 3, v[52:53]
	v_pk_add_f32 v[48:49], v[48:49], v[50:51]
	global_store_dwordx2 v[52:53], v[48:49], off
.LBB0_1707:
	s_or_b64 exec, exec, s[54:55]
	s_mov_b64 s[100:101], 0xb0000
	v_lshl_add_u64 v[218:219], v[220:221], 0, s[100:101]
	global_load_dwordx4 v[186:189], v[218:219], off
	global_load_dwordx4 v[190:193], v[218:219], off offset:16
	global_load_dwordx4 v[194:197], v[218:219], off offset:512
	global_load_dwordx4 v[198:201], v[218:219], off offset:528
	v_add_u32_e32 v48, 0x90, v144
	s_mov_b64 s[54:55], -1
	s_and_b64 vcc, exec, s[8:9]
	v_ashrrev_i32_e32 v49, 31, v48
	s_cbranch_vccnz .LBB0_1709
	v_readlane_b32 s36, v251, 3
	v_lshlrev_b64 v[50:51], 12, v[48:49]
	v_readlane_b32 s37, v251, 4
	s_mov_b64 s[54:55], 0
	v_readlane_b32 s38, v251, 5
	v_lshl_add_u64 v[52:53], s[36:37], 0, v[50:51]
	v_readlane_b32 s39, v251, 6
	v_readlane_b32 s40, v251, 7
	v_readlane_b32 s41, v251, 8
	v_readlane_b32 s42, v251, 9
	v_readlane_b32 s43, v251, 10
	v_readlane_b32 s44, v251, 11
	v_readlane_b32 s45, v251, 12
	v_readlane_b32 s46, v251, 13
	v_readlane_b32 s47, v251, 14
	v_readlane_b32 s48, v251, 15
	v_readlane_b32 s49, v251, 16
	v_readlane_b32 s50, v251, 17
	v_readlane_b32 s51, v251, 18

.LBB0_1711:
	v_lshl_add_u64 v[60:61], v[52:53], 0, v[146:147]
	v_lshl_add_u64 v[50:51], s[0:1], 0, v[50:51]
	v_lshl_add_u64 v[62:63], v[50:51], 0, v[146:147]
	s_waitcnt vmcnt(21)
	v_pk_fma_f32 v[46:47], v[204:205], s[26:27], v[46:47] op_sel_hi:[1,0,1]
	v_pk_fma_f32 v[44:45], v[202:203], s[26:27], v[44:45] op_sel_hi:[1,0,1]
	s_waitcnt vmcnt(20)
	v_pk_fma_f32 v[42:43], v[208:209], s[26:27], v[42:43] op_sel_hi:[1,0,1]
	v_pk_fma_f32 v[40:41], v[206:207], s[26:27], v[40:41] op_sel_hi:[1,0,1]
	global_store_dwordx4 v[62:63], v[44:47], off
	global_store_dwordx4 v[62:63], v[40:43], off offset:16
	v_add_f32_e32 v58, v44, v45
	v_add_f32_e32 v59, v46, v47
	v_mul_f32_e32 v45, v45, v45
	v_mul_f32_e32 v47, v47, v47
	v_add_f32_e32 v60, v40, v41
	v_add_f32_e32 v61, v42, v43
	v_mul_f32_e32 v41, v41, v41
	v_mul_f32_e32 v43, v43, v43
	v_fmac_f32_e32 v45, v44, v44
	v_fmac_f32_e32 v47, v46, v46
	v_fmac_f32_e32 v41, v40, v40
	v_fmac_f32_e32 v43, v42, v42
	v_add_f32_e32 v42, v45, v47
	v_add_f32_e32 v41, v42, v41
	v_add_f32_e32 v41, v43, v41
	v_add_f32_e32 v58, v58, v59
	v_add_f32_e32 v40, v58, v60
	v_add_f32_e32 v40, v61, v40
	v_add_f32_e32 v40, 0, v40
	s_waitcnt vmcnt(21)
	v_pk_fma_f32 v[38:39], v[212:213], s[26:27], v[38:39] op_sel_hi:[1,0,1]
	v_pk_fma_f32 v[36:37], v[210:211], s[26:27], v[36:37] op_sel_hi:[1,0,1]
	s_waitcnt vmcnt(20)
	v_pk_fma_f32 v[34:35], v[216:217], s[26:27], v[34:35] op_sel_hi:[1,0,1]
	v_pk_fma_f32 v[32:33], v[214:215], s[26:27], v[32:33] op_sel_hi:[1,0,1]
	global_store_dwordx4 v[62:63], v[36:39], off offset:512
	global_store_dwordx4 v[62:63], v[32:35], off offset:528
	v_add_f32_e32 v42, v36, v37
	v_add_f32_e32 v43, v38, v39
	v_mul_f32_e32 v37, v37, v37
	v_mul_f32_e32 v39, v39, v39
	v_add_f32_e32 v44, v32, v33
	v_add_f32_e32 v45, v34, v35
	v_mul_f32_e32 v33, v33, v33
	v_mul_f32_e32 v35, v35, v35
	v_fmac_f32_e32 v37, v36, v36
	v_fmac_f32_e32 v39, v38, v38
	v_add_f32_e32 v42, v42, v43
	v_fmac_f32_e32 v33, v32, v32
	v_fmac_f32_e32 v35, v34, v34
	v_add_f32_e32 v34, v37, v39
	v_add_f32_e32 v32, v42, v44
	v_add_f32_e32 v33, v34, v33
	v_add_f32_e32 v32, v45, v32
	v_add_f32_e32 v33, v35, v33
	v_add_f32_e32 v32, v40, v32
	v_add_f32_e32 v33, v41, v33
	v_mov_b32_e32 v34, v32
	v_mov_b32_e32 v35, v33
	s_nop 0
	v_permlane16_swap_b32_e32 v32, v34
	v_permlane16_swap_b32_e32 v33, v35
	v_add_f32_e32 v32, v32, v34
	v_add_f32_e32 v33, v33, v35
	v_mov_b32_e32 v34, v32
	v_mov_b32_e32 v35, v33
	s_nop 0
	v_permlane32_swap_b32_e32 v32, v34
	v_permlane32_swap_b32_e32 v33, v35
	s_and_saveexec_b64 s[54:55], s[4:5]
	s_cbranch_execz .LBB0_1713
	v_lshlrev_b64 v[36:37], 7, v[48:49]
	v_lshl_add_u64 v[36:37], s[14:15], 0, v[36:37]
	v_lshl_add_u64 v[36:37], s[52:53], 3, v[36:37]
	v_pk_add_f32 v[32:33], v[32:33], v[34:35]
	global_store_dwordx2 v[36:37], v[32:33], off

.LBB0_1717:
	v_lshl_add_u64 v[44:45], v[36:37], 0, v[146:147]
	v_lshl_add_u64 v[34:35], s[0:1], 0, v[34:35]
	v_lshl_add_u64 v[46:47], v[34:35], 0, v[146:147]
	s_waitcnt vmcnt(17)
	v_pk_fma_f32 v[30:31], v[172:173], s[26:27], v[30:31] op_sel_hi:[1,0,1]
	v_pk_fma_f32 v[28:29], v[170:171], s[26:27], v[28:29] op_sel_hi:[1,0,1]
	s_waitcnt vmcnt(16)
	v_pk_fma_f32 v[26:27], v[176:177], s[26:27], v[26:27] op_sel_hi:[1,0,1]
	v_pk_fma_f32 v[24:25], v[174:175], s[26:27], v[24:25] op_sel_hi:[1,0,1]
	global_store_dwordx4 v[46:47], v[28:31], off
	global_store_dwordx4 v[46:47], v[24:27], off offset:16
	v_add_f32_e32 v42, v28, v29
	v_add_f32_e32 v43, v30, v31
	v_mul_f32_e32 v29, v29, v29
	v_mul_f32_e32 v31, v31, v31
	v_add_f32_e32 v44, v24, v25
	v_add_f32_e32 v45, v26, v27
	v_mul_f32_e32 v25, v25, v25
	v_mul_f32_e32 v27, v27, v27
	v_fmac_f32_e32 v29, v28, v28
	v_fmac_f32_e32 v31, v30, v30
	v_fmac_f32_e32 v25, v24, v24
	v_fmac_f32_e32 v27, v26, v26
	v_add_f32_e32 v26, v29, v31
	v_add_f32_e32 v25, v26, v25
	v_add_f32_e32 v25, v27, v25
	v_add_f32_e32 v42, v42, v43
	v_add_f32_e32 v24, v42, v44
	v_add_f32_e32 v24, v45, v24
	v_add_f32_e32 v24, 0, v24
	s_waitcnt vmcnt(17)
	v_pk_fma_f32 v[22:23], v[180:181], s[26:27], v[22:23] op_sel_hi:[1,0,1]
	v_pk_fma_f32 v[20:21], v[178:179], s[26:27], v[20:21] op_sel_hi:[1,0,1]
	s_waitcnt vmcnt(16)
	v_pk_fma_f32 v[18:19], v[184:185], s[26:27], v[18:19] op_sel_hi:[1,0,1]
	v_pk_fma_f32 v[16:17], v[182:183], s[26:27], v[16:17] op_sel_hi:[1,0,1]
	global_store_dwordx4 v[46:47], v[20:23], off offset:512
	global_store_dwordx4 v[46:47], v[16:19], off offset:528
	v_add_f32_e32 v26, v20, v21
	v_add_f32_e32 v27, v22, v23
	v_mul_f32_e32 v21, v21, v21
	v_mul_f32_e32 v23, v23, v23
	v_add_f32_e32 v28, v16, v17
	v_add_f32_e32 v29, v18, v19
	v_mul_f32_e32 v17, v17, v17
	v_mul_f32_e32 v19, v19, v19
	v_fmac_f32_e32 v21, v20, v20
	v_fmac_f32_e32 v23, v22, v22
	v_add_f32_e32 v26, v26, v27
	v_fmac_f32_e32 v17, v16, v16
	v_fmac_f32_e32 v19, v18, v18
	v_add_f32_e32 v18, v21, v23
	v_add_f32_e32 v16, v26, v28
	v_add_f32_e32 v17, v18, v17
	v_add_f32_e32 v16, v29, v16
	v_add_f32_e32 v17, v19, v17
	v_add_f32_e32 v16, v24, v16
	v_add_f32_e32 v17, v25, v17
	v_mov_b32_e32 v18, v16
	v_mov_b32_e32 v19, v17
	s_nop 0
	v_permlane16_swap_b32_e32 v16, v18
	v_permlane16_swap_b32_e32 v17, v19
	v_add_f32_e32 v16, v16, v18
	v_add_f32_e32 v17, v17, v19
	v_mov_b32_e32 v18, v16
	v_mov_b32_e32 v19, v17
	s_nop 0
	v_permlane32_swap_b32_e32 v16, v18
	v_permlane32_swap_b32_e32 v17, v19
	s_and_saveexec_b64 s[54:55], s[4:5]
	s_cbranch_execz .LBB0_1719
	v_lshlrev_b64 v[20:21], 7, v[32:33]
	v_lshl_add_u64 v[20:21], s[14:15], 0, v[20:21]
	v_lshl_add_u64 v[20:21], s[52:53], 3, v[20:21]
	v_pk_add_f32 v[16:17], v[16:17], v[18:19]
	global_store_dwordx2 v[20:21], v[16:17], off

.LBB0_1723:
	v_lshl_add_u64 v[28:29], v[20:21], 0, v[146:147]
	v_lshl_add_u64 v[18:19], s[0:1], 0, v[18:19]
	v_lshl_add_u64 v[30:31], v[18:19], 0, v[146:147]
	s_waitcnt vmcnt(13)
	v_pk_fma_f32 v[14:15], v[188:189], s[26:27], v[14:15] op_sel_hi:[1,0,1]
	v_pk_fma_f32 v[12:13], v[186:187], s[26:27], v[12:13] op_sel_hi:[1,0,1]
	s_waitcnt vmcnt(12)
	v_pk_fma_f32 v[10:11], v[192:193], s[26:27], v[10:11] op_sel_hi:[1,0,1]
	v_pk_fma_f32 v[8:9], v[190:191], s[26:27], v[8:9] op_sel_hi:[1,0,1]
	global_store_dwordx4 v[30:31], v[12:15], off
	global_store_dwordx4 v[30:31], v[8:11], off offset:16
	v_add_f32_e32 v26, v12, v13
	v_add_f32_e32 v27, v14, v15
	v_mul_f32_e32 v13, v13, v13
	v_mul_f32_e32 v15, v15, v15
	v_add_f32_e32 v28, v8, v9
	v_add_f32_e32 v29, v10, v11
	v_mul_f32_e32 v9, v9, v9
	v_mul_f32_e32 v11, v11, v11
	v_fmac_f32_e32 v13, v12, v12
	v_fmac_f32_e32 v15, v14, v14
	v_fmac_f32_e32 v9, v8, v8
	v_fmac_f32_e32 v11, v10, v10
	v_add_f32_e32 v10, v13, v15
	v_add_f32_e32 v9, v10, v9
	v_add_f32_e32 v9, v11, v9
	v_add_f32_e32 v26, v26, v27
	v_add_f32_e32 v8, v26, v28
	v_add_f32_e32 v8, v29, v8
	v_add_f32_e32 v8, 0, v8
	s_waitcnt vmcnt(13)
	v_pk_fma_f32 v[6:7], v[196:197], s[26:27], v[6:7] op_sel_hi:[1,0,1]
	v_pk_fma_f32 v[4:5], v[194:195], s[26:27], v[4:5] op_sel_hi:[1,0,1]
	s_waitcnt vmcnt(12)
	v_pk_fma_f32 v[2:3], v[200:201], s[26:27], v[2:3] op_sel_hi:[1,0,1]
	v_pk_fma_f32 v[0:1], v[198:199], s[26:27], v[0:1] op_sel_hi:[1,0,1]
	global_store_dwordx4 v[30:31], v[4:7], off offset:512
	global_store_dwordx4 v[30:31], v[0:3], off offset:528
	v_add_f32_e32 v10, v4, v5
	v_add_f32_e32 v11, v6, v7
	v_mul_f32_e32 v5, v5, v5
	v_mul_f32_e32 v7, v7, v7
	v_add_f32_e32 v12, v0, v1
	v_add_f32_e32 v13, v2, v3
	v_mul_f32_e32 v1, v1, v1
	v_mul_f32_e32 v3, v3, v3
	v_fmac_f32_e32 v5, v4, v4
	v_fmac_f32_e32 v7, v6, v6
	v_add_f32_e32 v10, v10, v11
	v_fmac_f32_e32 v1, v0, v0
	v_fmac_f32_e32 v3, v2, v2
	v_add_f32_e32 v2, v5, v7
	v_add_f32_e32 v0, v10, v12
	v_add_f32_e32 v1, v2, v1
	v_add_f32_e32 v0, v13, v0
	v_add_f32_e32 v1, v3, v1
	v_add_f32_e32 v0, v8, v0
	v_add_f32_e32 v1, v9, v1
	v_mov_b32_e32 v2, v0
	v_mov_b32_e32 v3, v1
	s_nop 0
	v_permlane16_swap_b32_e32 v0, v2
	v_permlane16_swap_b32_e32 v1, v3
	v_add_f32_e32 v0, v0, v2
	v_add_f32_e32 v1, v1, v3
	v_mov_b32_e32 v2, v0
	v_mov_b32_e32 v3, v1
	s_nop 0
	v_permlane32_swap_b32_e32 v0, v2
	v_permlane32_swap_b32_e32 v1, v3
	s_and_saveexec_b64 s[8:9], s[4:5]
	s_cbranch_execz .LBB0_1725
	v_lshlrev_b64 v[4:5], 7, v[16:17]
	v_lshl_add_u64 v[4:5], s[14:15], 0, v[4:5]
	v_lshl_add_u64 v[4:5], s[52:53], 3, v[4:5]
	v_pk_add_f32 v[0:1], v[0:1], v[2:3]
	global_store_dwordx2 v[4:5], v[0:1], off
